# same as previous best; MFMA-result read distance in P6 cross-term padded to the full 12 wait states
# speedup vs baseline: 1.0035x; 1.0035x over previous
; __device__ __forceinline__ int crow(int r, int hi) { return (r & 3) + 8 * (r >> 2) + 4 * hi; }
; #define MFMA32(a, b, c) __builtin_amdgcn_mfma_f32_32x32x16_bf16((a), (b), (c), 0, 0, 0)
; __device__ __forceinline__ void ro_item2(int it0, LAS unsigned char* lds, const bf16_t* RQ, const bf16_t* RK, const bf16_t* RV, const bf16_t* RG, const bf16_t* SPREV, const float* GN, bf16_t* MIX,
;                                          int tid, int wid, int lane) {
;     ...
;     for (int jt = 0; jt <= ct; ++jt) {
;         f32x16 st = {};
;         const bf16_t* kptr = RK + (r0 + 32 * jt + x) * 1024 + h * 128 + 8 * hi;
; #pragma unroll
;         for (int ks = 0; ks < 8; ++ks) st = MFMA32(*(const bf16x8*)(kptr + 16 * ks), qf[ks], st);
;         if (jt == ct) {
; #pragma unroll
;             for (int r = 0; r < 16; ++r) if (crow(r, hi) > x) st[r] = 0.f;
;         }
; #pragma unroll
;         for (int s2 = 0; s2 < 2; ++s2) {
;             const bf16x8 pb = pack8(st, s2);
; #pragma unroll
;             for (int et = 0; et < 4; ++et) o[et] = MFMA32(lds_cat_sw<VS>(VT, 32 * et + x, 32 * jt + 16 * s2 + 4 * hi), pb, o[et]);
;         }
;     }
;     const bf16_t* sp = SPREV + (size_t)it * 16384;
; #pragma unroll
;     for (int et = 0; et < 4; ++et)
; #pragma unroll
;         for (int ks = 0; ks < 8; ++ks) o[et] = MFMA32(*(const bf16x8*)(sp + (32 * et + x) * 128 + 16 * ks + 8 * hi), qf[ks], o[et]);
.LBB0_1219:
	v_mov_b32_e32 v68, s53
	v_or3_b32 v69, s48, 0, 0
	v_or3_b32 v68, s35, v126, v68
	v_lshl_add_u64 v[66:67], v[130:131], 0, s[42:43]
	v_lshlrev_b64 v[68:69], 11, v[68:69]
	v_lshl_add_u64 v[146:147], v[66:67], 0, v[68:69]
	s_ashr_i32 s35, s34, 31
	s_lshl_b64 s[34:35], s[34:35], 15
	s_add_i32 s50, s50, s54
	s_add_i32 s55, s55, s56
	s_add_i32 s57, s57, s58
	s_mov_b64 s[100:101], 0x2000
	v_lshl_add_u64 v[184:185], v[134:135], 0, s[34:35]
	v_lshl_add_u64 v[186:187], v[184:185], 0, s[100:101]
	v_lshl_add_u64 v[188:189], v[186:187], 0, s[100:101]
	v_lshl_add_u64 v[252:253], v[188:189], 0, s[100:101]
	global_load_dwordx4 v[192:195], v[184:185], off
	global_load_dwordx4 v[196:199], v[184:185], off offset:32
	global_load_dwordx4 v[200:203], v[184:185], off offset:64
	global_load_dwordx4 v[204:207], v[184:185], off offset:96
	global_load_dwordx4 v[208:211], v[184:185], off offset:128
	global_load_dwordx4 v[212:215], v[184:185], off offset:160
	global_load_dwordx4 v[216:219], v[184:185], off offset:192
	global_load_dwordx4 v[220:223], v[146:147], off
	global_load_dwordx4 v[224:227], v[146:147], off offset:32
	global_load_dwordx4 v[228:231], v[146:147], off offset:64
	global_load_dwordx4 v[232:235], v[146:147], off offset:96
	global_load_dwordx4 v[236:239], v[146:147], off offset:128
	global_load_dwordx4 v[240:243], v[146:147], off offset:160
	global_load_dwordx4 v[244:247], v[146:147], off offset:192
	global_load_dwordx4 v[248:251], v[146:147], off offset:224
	s_waitcnt vmcnt(7)
	v_mfma_f32_32x32x16_bf16 v[66:81], v[220:223], v[110:113], 0
	s_waitcnt vmcnt(6)
	v_mfma_f32_32x32x16_bf16 v[66:81], v[224:227], v[106:109], v[66:81]
	s_waitcnt vmcnt(5)
	v_mfma_f32_32x32x16_bf16 v[66:81], v[228:231], v[102:105], v[66:81]
	s_waitcnt vmcnt(4)
	v_mfma_f32_32x32x16_bf16 v[66:81], v[232:235], v[98:101], v[66:81]
	s_waitcnt vmcnt(3)
	v_mfma_f32_32x32x16_bf16 v[66:81], v[236:239], v[94:97], v[66:81]
	s_waitcnt vmcnt(2)
	v_mfma_f32_32x32x16_bf16 v[66:81], v[240:243], v[90:93], v[66:81]
	s_waitcnt vmcnt(1)
	v_mfma_f32_32x32x16_bf16 v[66:81], v[244:247], v[86:89], v[66:81]
	s_waitcnt vmcnt(0)
	v_mfma_f32_32x32x16_bf16 v[66:81], v[248:251], v[82:85], v[66:81]
	global_load_dwordx4 v[220:223], v[184:185], off offset:224
	global_load_dwordx4 v[224:227], v[186:187], off
	global_load_dwordx4 v[228:231], v[186:187], off offset:32
	global_load_dwordx4 v[232:235], v[186:187], off offset:64
	global_load_dwordx4 v[236:239], v[186:187], off offset:96
	global_load_dwordx4 v[240:243], v[186:187], off offset:128
	global_load_dwordx4 v[244:247], v[186:187], off offset:160
	global_load_dwordx4 v[248:251], v[186:187], off offset:192
	s_nop 11
	v_cndmask_b32_e64 v141, v66, 0, s[0:1]
	v_cndmask_b32_e64 v66, v141, v66, s[2:3]
	v_cndmask_b32_e64 v67, 0, v67, s[2:3]
	v_cndmask_b32_e64 v68, v68, 0, s[4:5]
	v_cndmask_b32_e64 v69, v69, 0, s[6:7]
	v_cndmask_b32_e64 v70, v70, 0, s[8:9]
	v_cndmask_b32_e64 v71, v71, 0, s[10:11]
	v_cndmask_b32_e64 v72, v72, 0, s[12:13]
	v_cndmask_b32_e64 v73, v73, 0, s[14:15]
	v_cvt_pk_bf16_f32 v66, v66, v67
	v_cvt_pk_bf16_f32 v67, v68, v69
	v_cvt_pk_bf16_f32 v68, v70, v71
	v_cvt_pk_bf16_f32 v69, v72, v73
	ds_read_b64 v[70:71], v157
	ds_read_b64 v[72:73], v158
	s_waitcnt lgkmcnt(0)
	v_mfma_f32_32x32x16_bf16 v[50:65], v[70:73], v[66:69], v[50:65]
	ds_read_b64 v[70:71], v159
	ds_read_b64 v[72:73], v160
	v_cndmask_b32_e64 v74, v74, 0, s[16:17]
	v_cndmask_b32_e64 v75, v75, 0, s[18:19]
	v_cndmask_b32_e64 v76, v76, 0, s[20:21]
	v_cndmask_b32_e64 v77, v77, 0, s[22:23]
	v_cndmask_b32_e64 v78, v78, 0, s[24:25]
	v_cndmask_b32_e64 v79, v79, 0, s[26:27]
	s_waitcnt lgkmcnt(0)
	v_mfma_f32_32x32x16_bf16 v[34:49], v[70:73], v[66:69], v[34:49]
	ds_read_b64 v[70:71], v161
	ds_read_b64 v[72:73], v162
	v_cndmask_b32_e64 v80, v80, 0, s[28:29]
	v_cndmask_b32_e64 v81, v81, 0, s[30:31]
	v_mov_b32_e32 v141, v115
	s_waitcnt lgkmcnt(0)
	v_mfma_f32_32x32x16_bf16 v[18:33], v[70:73], v[66:69], v[18:33]
	ds_read_b64 v[70:71], v163
	ds_read_b64 v[72:73], v164
	s_waitcnt lgkmcnt(0)
	v_mfma_f32_32x32x16_bf16 v[2:17], v[70:73], v[66:69], v[2:17]
	ds_read_b64 v[70:71], v165
	ds_read_b64 v[72:73], v166
	v_cvt_pk_bf16_f32 v66, v74, v75
	v_cvt_pk_bf16_f32 v67, v76, v77
	v_cvt_pk_bf16_f32 v68, v78, v79
	v_cvt_pk_bf16_f32 v69, v80, v81
	s_waitcnt lgkmcnt(0)
	s_nop 0
	v_mfma_f32_32x32x16_bf16 v[50:65], v[70:73], v[66:69], v[50:65]
	ds_read_b64 v[70:71], v167
	ds_read_b64 v[72:73], v168
	s_waitcnt lgkmcnt(0)
	v_mfma_f32_32x32x16_bf16 v[34:49], v[70:73], v[66:69], v[34:49]
	ds_read_b64 v[70:71], v169
	ds_read_b64 v[72:73], v170
	s_waitcnt lgkmcnt(0)
	v_mfma_f32_32x32x16_bf16 v[18:33], v[70:73], v[66:69], v[18:33]
	ds_read_b64 v[70:71], v171
	ds_read_b64 v[72:73], v172
	s_waitcnt lgkmcnt(0)
	v_mfma_f32_32x32x16_bf16 v[2:17], v[70:73], v[66:69], v[2:17]
	s_waitcnt vmcnt(14)
	v_mfma_f32_32x32x16_bf16 v[50:65], v[192:195], v[110:113], v[50:65]
	global_load_dwordx4 v[192:195], v[186:187], off offset:224
	s_waitcnt vmcnt(14)
	v_mfma_f32_32x32x16_bf16 v[50:65], v[196:199], v[106:109], v[50:65]
	global_load_dwordx4 v[196:199], v[188:189], off
	s_waitcnt vmcnt(14)
	v_mfma_f32_32x32x16_bf16 v[50:65], v[200:203], v[102:105], v[50:65]
	global_load_dwordx4 v[200:203], v[188:189], off offset:32
	s_waitcnt vmcnt(14)
	v_mfma_f32_32x32x16_bf16 v[50:65], v[204:207], v[98:101], v[50:65]
	global_load_dwordx4 v[204:207], v[188:189], off offset:64
	s_waitcnt vmcnt(14)
	v_mfma_f32_32x32x16_bf16 v[50:65], v[208:211], v[94:97], v[50:65]
	global_load_dwordx4 v[208:211], v[188:189], off offset:96
	s_waitcnt vmcnt(14)
	v_mfma_f32_32x32x16_bf16 v[50:65], v[212:215], v[90:93], v[50:65]
	global_load_dwordx4 v[212:215], v[188:189], off offset:128
	s_waitcnt vmcnt(14)
; #define MFMA32(a, b, c) __builtin_amdgcn_mfma_f32_32x32x16_bf16((a), (b), (c), 0, 0, 0)
; __device__ __forceinline__ void ro_item2(int it0, LAS unsigned char* lds, const bf16_t* RQ, const bf16_t* RK, const bf16_t* RV, const bf16_t* RG, const bf16_t* SPREV, const float* GN, bf16_t* MIX,
;                                          int tid, int wid, int lane) {
;     ...
;     const bf16_t* sp = SPREV + (size_t)it * 16384;
; #pragma unroll
;     for (int et = 0; et < 4; ++et)
; #pragma unroll
;         for (int ks = 0; ks < 8; ++ks) o[et] = MFMA32(*(const bf16x8*)(sp + (32 * et + x) * 128 + 16 * ks + 8 * hi), qf[ks], o[et]);
;     float s1 = 0.f, s2 = 0.f;
; #pragma unroll
;     for (int et = 0; et < 4; ++et)
; #pragma unroll
;         for (int r = 0; r < 16; ++r) { s1 += o[et][r]; s2 += o[et][r] * o[et][r]; }
	v_mfma_f32_32x32x16_bf16 v[50:65], v[216:219], v[86:89], v[50:65]
	global_load_dwordx4 v[216:219], v[188:189], off offset:160
	s_waitcnt vmcnt(14)
	v_mfma_f32_32x32x16_bf16 v[50:65], v[220:223], v[82:85], v[50:65]
	global_load_dwordx4 v[220:223], v[188:189], off offset:192
	s_waitcnt vmcnt(14)
	v_mfma_f32_32x32x16_bf16 v[34:49], v[224:227], v[110:113], v[34:49]
	global_load_dwordx4 v[224:227], v[188:189], off offset:224
	s_nop 10
	v_mul_f32_e32 v80, v51, v51
	v_fmac_f32_e32 v80, v50, v50
	v_fmac_f32_e32 v80, v52, v52
	v_fmac_f32_e32 v80, v53, v53
	v_fmac_f32_e32 v80, v54, v54
	v_fmac_f32_e32 v80, v55, v55
	v_fmac_f32_e32 v80, v56, v56
	v_fmac_f32_e32 v80, v57, v57
	v_fmac_f32_e32 v80, v58, v58
	v_fmac_f32_e32 v80, v59, v59
	v_fmac_f32_e32 v80, v60, v60
	v_fmac_f32_e32 v80, v61, v61
	v_fmac_f32_e32 v80, v62, v62
	v_fmac_f32_e32 v80, v63, v63
	v_fmac_f32_e32 v80, v64, v64
	v_fmac_f32_e32 v80, v65, v65
	s_waitcnt vmcnt(14)
	v_mfma_f32_32x32x16_bf16 v[34:49], v[228:231], v[106:109], v[34:49]
	global_load_dwordx4 v[228:231], v[252:253], off
	s_waitcnt vmcnt(14)
	v_mfma_f32_32x32x16_bf16 v[34:49], v[232:235], v[102:105], v[34:49]
	global_load_dwordx4 v[232:235], v[252:253], off offset:32
	s_waitcnt vmcnt(14)
	v_mfma_f32_32x32x16_bf16 v[34:49], v[236:239], v[98:101], v[34:49]
	global_load_dwordx4 v[236:239], v[252:253], off offset:64
	s_waitcnt vmcnt(14)
	v_mfma_f32_32x32x16_bf16 v[34:49], v[240:243], v[94:97], v[34:49]
	global_load_dwordx4 v[240:243], v[252:253], off offset:96
	s_waitcnt vmcnt(14)
	v_mfma_f32_32x32x16_bf16 v[34:49], v[244:247], v[90:93], v[34:49]
	global_load_dwordx4 v[244:247], v[252:253], off offset:128
	s_waitcnt vmcnt(14)
	v_mfma_f32_32x32x16_bf16 v[34:49], v[248:251], v[86:89], v[34:49]
	global_load_dwordx4 v[248:251], v[252:253], off offset:160
	s_waitcnt vmcnt(14)
	v_mfma_f32_32x32x16_bf16 v[34:49], v[192:195], v[82:85], v[34:49]
	global_load_dwordx4 v[192:195], v[252:253], off offset:192
	s_waitcnt vmcnt(14)
	v_mfma_f32_32x32x16_bf16 v[18:33], v[196:199], v[110:113], v[18:33]
	global_load_dwordx4 v[196:199], v[252:253], off offset:224
	s_nop 10
	v_fmac_f32_e32 v80, v34, v34
	v_fmac_f32_e32 v80, v35, v35
	v_fmac_f32_e32 v80, v36, v36
	v_fmac_f32_e32 v80, v37, v37
	v_fmac_f32_e32 v80, v38, v38
	v_fmac_f32_e32 v80, v39, v39
	v_fmac_f32_e32 v80, v40, v40
	v_fmac_f32_e32 v80, v41, v41
	v_fmac_f32_e32 v80, v42, v42
	v_fmac_f32_e32 v80, v43, v43
	v_fmac_f32_e32 v80, v44, v44
	v_fmac_f32_e32 v80, v45, v45
	v_fmac_f32_e32 v80, v46, v46
	v_fmac_f32_e32 v80, v47, v47
	v_fmac_f32_e32 v80, v48, v48
	v_fmac_f32_e32 v80, v49, v49
	s_waitcnt vmcnt(14)
	v_mfma_f32_32x32x16_bf16 v[18:33], v[200:203], v[106:109], v[18:33]
	s_waitcnt vmcnt(13)
	v_mfma_f32_32x32x16_bf16 v[18:33], v[204:207], v[102:105], v[18:33]
	s_waitcnt vmcnt(12)
	v_mfma_f32_32x32x16_bf16 v[18:33], v[208:211], v[98:101], v[18:33]
	s_waitcnt vmcnt(11)
	v_mfma_f32_32x32x16_bf16 v[18:33], v[212:215], v[94:97], v[18:33]
	s_waitcnt vmcnt(10)
	v_mfma_f32_32x32x16_bf16 v[18:33], v[216:219], v[90:93], v[18:33]
	s_waitcnt vmcnt(9)
	v_mfma_f32_32x32x16_bf16 v[18:33], v[220:223], v[86:89], v[18:33]
	s_waitcnt vmcnt(8)
	v_mfma_f32_32x32x16_bf16 v[18:33], v[224:227], v[82:85], v[18:33]
	s_waitcnt vmcnt(7)
	v_mfma_f32_32x32x16_bf16 v[2:17], v[228:231], v[110:113], v[2:17]
	s_nop 10
	v_fmac_f32_e32 v80, v18, v18
	v_fmac_f32_e32 v80, v19, v19
	v_fmac_f32_e32 v80, v20, v20
	v_fmac_f32_e32 v80, v21, v21
	v_fmac_f32_e32 v80, v22, v22
	v_fmac_f32_e32 v80, v23, v23
	v_fmac_f32_e32 v80, v24, v24
	v_fmac_f32_e32 v80, v25, v25
	v_fmac_f32_e32 v80, v26, v26
	v_fmac_f32_e32 v80, v27, v27
	v_fmac_f32_e32 v80, v28, v28
	v_fmac_f32_e32 v80, v29, v29
	v_fmac_f32_e32 v80, v30, v30
	v_fmac_f32_e32 v80, v31, v31
	v_fmac_f32_e32 v80, v32, v32
	v_fmac_f32_e32 v80, v33, v33
	s_waitcnt vmcnt(6)
	v_mfma_f32_32x32x16_bf16 v[2:17], v[232:235], v[106:109], v[2:17]
	s_waitcnt vmcnt(5)
	v_mfma_f32_32x32x16_bf16 v[2:17], v[236:239], v[102:105], v[2:17]
	s_waitcnt vmcnt(4)
	v_mfma_f32_32x32x16_bf16 v[2:17], v[240:243], v[98:101], v[2:17]
	s_waitcnt vmcnt(3)
	v_mfma_f32_32x32x16_bf16 v[2:17], v[244:247], v[94:97], v[2:17]
	s_waitcnt vmcnt(2)
	v_mfma_f32_32x32x16_bf16 v[2:17], v[248:251], v[90:93], v[2:17]
	s_waitcnt vmcnt(1)
	v_mfma_f32_32x32x16_bf16 v[2:17], v[192:195], v[86:89], v[2:17]
	s_waitcnt vmcnt(0)
; __device__ __forceinline__ void ro_item2(int it0, LAS unsigned char* lds, const bf16_t* RQ, const bf16_t* RK, const bf16_t* RV, const bf16_t* RG, const bf16_t* SPREV, const float* GN, bf16_t* MIX,
;                                          int tid, int wid, int lane) {
;     ...
;     float s1 = 0.f, s2 = 0.f;
; #pragma unroll
;     for (int et = 0; et < 4; ++et)
; #pragma unroll
;         for (int r = 0; r < 16; ++r) { s1 += o[et][r]; s2 += o[et][r] * o[et][r]; }
;     s1 += __shfl_xor(s1, 32); s2 += __shfl_xor(s2, 32);
;     const float mean = s1 * (1.0f / 128.0f), var = fmaxf(s2 * (1.0f / 128.0f) - mean * mean, 0.f), rstd = rsqrtf(var + EPS);
; #pragma unroll
;     for (int et = 0; et < 4; ++et)
; #pragma unroll
;         for (int g = 0; g < 4; ++g) {
;             const int e0 = 32 * et + 8 * g + 4 * hi;
;             const u32x2 gt = *(const u32x2*)(RG + qrow * 1024 + h * 128 + e0);
;             const f32x4 gn = *(const f32x4*)(GN + h * 128 + e0);
	v_mfma_f32_32x32x16_bf16 v[2:17], v[196:199], v[82:85], v[2:17]
	s_brev_b32 s34, 60
	v_add_f32_e32 v66, 0, v50
	v_add_f32_e32 v66, v51, v66
	v_add_f32_e32 v66, v52, v66
	v_add_f32_e32 v66, v53, v66
	v_add_f32_e32 v66, v54, v66
	v_add_f32_e32 v66, v55, v66
	v_add_f32_e32 v66, v56, v66
	v_add_f32_e32 v66, v57, v66
	v_add_f32_e32 v66, v58, v66
	v_add_f32_e32 v66, v59, v66
	v_add_f32_e32 v66, v60, v66
	v_add_f32_e32 v66, v61, v66
	v_add_f32_e32 v66, v62, v66
	v_add_f32_e32 v66, v63, v66
	v_add_f32_e32 v66, v64, v66
	v_add_f32_e32 v66, v65, v66
	v_add_f32_e32 v66, v66, v34
	v_add_f32_e32 v66, v35, v66
	v_add_f32_e32 v66, v36, v66
	v_add_f32_e32 v66, v37, v66
	v_add_f32_e32 v66, v38, v66
	v_add_f32_e32 v66, v39, v66
	v_add_f32_e32 v66, v40, v66
	v_add_f32_e32 v66, v41, v66
	v_add_f32_e32 v66, v42, v66
	v_add_f32_e32 v66, v43, v66
	v_add_f32_e32 v66, v44, v66
	v_add_f32_e32 v66, v45, v66
	v_add_f32_e32 v66, v46, v66
	v_add_f32_e32 v66, v47, v66
	v_add_f32_e32 v66, v48, v66
	v_add_f32_e32 v66, v49, v66
	v_add_f32_e32 v66, v66, v18
	v_add_f32_e32 v66, v19, v66
	v_add_f32_e32 v66, v20, v66
	v_add_f32_e32 v66, v21, v66
	v_add_f32_e32 v66, v22, v66
	v_add_f32_e32 v66, v23, v66
	v_add_f32_e32 v66, v24, v66
	v_add_f32_e32 v66, v25, v66
	v_add_f32_e32 v66, v26, v66
	v_add_f32_e32 v66, v27, v66
	v_add_f32_e32 v66, v28, v66
	v_add_f32_e32 v66, v29, v66
	v_add_f32_e32 v66, v30, v66
	v_add_f32_e32 v66, v31, v66
	v_add_f32_e32 v66, v32, v66
	v_add_f32_e32 v66, v33, v66
	v_add_f32_e32 v66, v66, v2
	v_add_f32_e32 v66, v3, v66
	v_fmac_f32_e32 v80, v2, v2
	v_add_f32_e32 v66, v4, v66
	v_fmac_f32_e32 v80, v3, v3
	v_add_f32_e32 v66, v5, v66
	v_fmac_f32_e32 v80, v4, v4
	v_add_f32_e32 v81, v6, v66
	v_pk_mul_f32 v[66:67], v[16:17], v[16:17]
	v_pk_mul_f32 v[78:79], v[4:5], v[4:5]
	v_pk_mul_f32 v[76:77], v[6:7], v[6:7]
	v_add_f32_e32 v67, v79, v80
	v_add_f32_e32 v67, v76, v67
	v_pk_mul_f32 v[74:75], v[8:9], v[8:9]
	v_add_f32_e32 v76, v7, v81
	v_add_f32_e32 v67, v77, v67
	v_add_f32_e32 v76, v8, v76
	v_add_f32_e32 v67, v74, v67
	v_pk_mul_f32 v[72:73], v[10:11], v[10:11]
	v_add_f32_e32 v74, v9, v76
	v_add_f32_e32 v67, v75, v67
	v_add_f32_e32 v74, v10, v74
	v_add_f32_e32 v67, v72, v67
	v_pk_mul_f32 v[70:71], v[12:13], v[12:13]
	v_add_f32_e32 v72, v11, v74
	v_add_f32_e32 v67, v73, v67
	v_add_f32_e32 v72, v12, v72
	v_add_f32_e32 v67, v70, v67
	v_pk_mul_f32 v[68:69], v[14:15], v[14:15]
	v_add_f32_e32 v70, v13, v72
	v_add_f32_e32 v67, v71, v67
	v_add_f32_e32 v70, v14, v70
	v_add_f32_e32 v68, v68, v67
	v_add_f32_e32 v67, v15, v70
	v_add_f32_e32 v68, v69, v68
	v_add_f32_e32 v67, v16, v67
	v_add_f32_e32 v68, v66, v68
	v_mul_f32_e32 v66, v17, v17
	v_mov_b32_e32 v69, v17
	v_pk_add_f32 v[66:67], v[68:69], v[66:67]
	ds_bpermute_b32 v69, v173, v67
	ds_bpermute_b32 v68, v173, v66
	s_waitcnt lgkmcnt(0)
	v_pk_add_f32 v[66:67], v[66:67], v[68:69]
	s_nop 0
	v_pk_mul_f32 v[70:71], v[66:67], s[34:35] op_sel_hi:[1,0]
	s_mov_b32 s34, 0x800000
	v_fma_f32 v66, -v71, v71, v70
	v_max_f32_e32 v66, 0, v66
	v_add_f32_e32 v66, 0x358637bd, v66
	v_cmp_gt_f32_e32 vcc, s34, v66
	v_mul_f32_e32 v67, 0x4b800000, v66
	v_readlane_b32 s34, v254, 54
	v_cndmask_b32_e32 v66, v66, v67, vcc
	v_rsq_f32_e32 v66, v66
	v_readlane_b32 s35, v254, 55
	v_lshlrev_b64 v[68:69], 12, v[142:143]
	v_lshl_add_u64 v[68:69], s[38:39], 0, v[68:69]
	v_mul_f32_e32 v67, 0x45800000, v66
	v_cndmask_b32_e32 v72, v66, v67, vcc
	v_lshl_add_u64 v[66:67], s[34:35], 0, v[144:145]
	v_lshl_add_u64 v[66:67], v[66:67], 0, s[42:43]
	v_lshl_add_u64 v[78:79], v[68:69], 0, s[42:43]
	s_lshl_b32 s42, s33, 2
	v_lshl_add_u64 v[76:77], v[66:67], 0, v[140:141]
	v_lshl_add_u64 v[74:75], v[136:137], 0, s[42:43]
	global_load_dwordx2 v[82:83], v[76:77], off
	global_load_dwordx4 v[192:195], v[74:75], off
	global_load_dwordx2 v[84:85], v[76:77], off offset:16
	global_load_dwordx4 v[196:199], v[74:75], off offset:32
	global_load_dwordx2 v[86:87], v[76:77], off offset:32
	global_load_dwordx4 v[200:203], v[74:75], off offset:64
	global_load_dwordx2 v[88:89], v[76:77], off offset:48
	global_load_dwordx4 v[204:207], v[74:75], off offset:96
	global_load_dwordx2 v[90:91], v[76:77], off offset:64
	global_load_dwordx4 v[208:211], v[74:75], off offset:128
	global_load_dwordx2 v[92:93], v[76:77], off offset:80
	global_load_dwordx4 v[212:215], v[74:75], off offset:160
	global_load_dwordx2 v[94:95], v[76:77], off offset:96
	global_load_dwordx4 v[216:219], v[74:75], off offset:192
	global_load_dwordx2 v[96:97], v[76:77], off offset:112
	global_load_dwordx4 v[220:223], v[74:75], off offset:224
	global_load_dwordx2 v[98:99], v[76:77], off offset:128
	global_load_dwordx4 v[224:227], v[74:75], off offset:256
	global_load_dwordx2 v[100:101], v[76:77], off offset:144
	global_load_dwordx4 v[228:231], v[74:75], off offset:288
	global_load_dwordx2 v[102:103], v[76:77], off offset:160
	global_load_dwordx4 v[232:235], v[74:75], off offset:320
	global_load_dwordx2 v[104:105], v[76:77], off offset:176
	global_load_dwordx4 v[236:239], v[74:75], off offset:352
	global_load_dwordx2 v[106:107], v[76:77], off offset:192
	global_load_dwordx4 v[240:243], v[74:75], off offset:384
	global_load_dwordx2 v[108:109], v[76:77], off offset:208
	global_load_dwordx4 v[244:247], v[74:75], off offset:416
	global_load_dwordx2 v[110:111], v[76:77], off offset:224
	global_load_dwordx4 v[248:251], v[74:75], off offset:448
	global_load_dwordx2 v[112:113], v[76:77], off offset:240
	global_load_dwordx4 v[180:183], v[74:75], off offset:480
	v_pk_add_f32 v[50:51], v[50:51], v[70:71] op_sel:[0,1] neg_lo:[0,1] neg_hi:[0,1]
	v_pk_add_f32 v[52:53], v[52:53], v[70:71] op_sel:[0,1] neg_lo:[0,1] neg_hi:[0,1]
; __device__ __forceinline__ unsigned cvtpk(float lo, float hi) { f32x2_t v = {lo, hi}; bf16x2_t b = __builtin_convertvector(v, bf16x2_t); return __builtin_bit_cast(unsigned, b); }
; __device__ __forceinline__ float bflo(unsigned w) { return __uint_as_float(w << 16); }
; __device__ __forceinline__ float bfhi(unsigned w) { return __uint_as_float(w & 0xffff0000u); }
; __device__ __forceinline__ void ro_item2(int it0, LAS unsigned char* lds, const bf16_t* RQ, const bf16_t* RK, const bf16_t* RV, const bf16_t* RG, const bf16_t* SPREV, const float* GN, bf16_t* MIX,
;                                          int tid, int wid, int lane) {
;     ...
; #pragma unroll
;     for (int et = 0; et < 4; ++et)
; #pragma unroll
;         for (int g = 0; g < 4; ++g) {
;             const int e0 = 32 * et + 8 * g + 4 * hi;
;             const u32x2 gt = *(const u32x2*)(RG + qrow * 1024 + h * 128 + e0);
;             const f32x4 gn = *(const f32x4*)(GN + h * 128 + e0);
;             const float y0 = (o[et][4 * g] - mean) * rstd * gn[0] * bflo(gt.x), y1 = (o[et][4 * g + 1] - mean) * rstd * gn[1] * bfhi(gt.x);
;             const float y2 = (o[et][4 * g + 2] - mean) * rstd * gn[2] * bflo(gt.y), y3 = (o[et][4 * g + 3] - mean) * rstd * gn[3] * bfhi(gt.y);
;             u32x2 w; w.x = cvtpk(y0, y1); w.y = cvtpk(y2, y3);
;             *(u32x2*)(MIX + qrow * 2048 + h * 128 + e0) = w;
;         }
	v_pk_mul_f32 v[50:51], v[50:51], v[72:73] op_sel_hi:[1,0]
	v_pk_mul_f32 v[52:53], v[52:53], v[72:73] op_sel_hi:[1,0]
	v_pk_add_f32 v[54:55], v[54:55], v[70:71] op_sel:[0,1] neg_lo:[0,1] neg_hi:[0,1]
	v_pk_add_f32 v[56:57], v[56:57], v[70:71] op_sel:[0,1] neg_lo:[0,1] neg_hi:[0,1]
	v_pk_mul_f32 v[54:55], v[54:55], v[72:73] op_sel_hi:[1,0]
	v_pk_mul_f32 v[56:57], v[56:57], v[72:73] op_sel_hi:[1,0]
	v_pk_add_f32 v[58:59], v[58:59], v[70:71] op_sel:[0,1] neg_lo:[0,1] neg_hi:[0,1]
	v_pk_add_f32 v[34:35], v[34:35], v[70:71] op_sel:[0,1] neg_lo:[0,1] neg_hi:[0,1]
	v_pk_mul_f32 v[58:59], v[58:59], v[72:73] op_sel_hi:[1,0]
	v_pk_mul_f32 v[34:35], v[34:35], v[72:73] op_sel_hi:[1,0]
	v_pk_add_f32 v[36:37], v[36:37], v[70:71] op_sel:[0,1] neg_lo:[0,1] neg_hi:[0,1]
	v_pk_add_f32 v[38:39], v[38:39], v[70:71] op_sel:[0,1] neg_lo:[0,1] neg_hi:[0,1]
	v_pk_mul_f32 v[36:37], v[36:37], v[72:73] op_sel_hi:[1,0]
	v_pk_mul_f32 v[38:39], v[38:39], v[72:73] op_sel_hi:[1,0]
	v_pk_add_f32 v[18:19], v[18:19], v[70:71] op_sel:[0,1] neg_lo:[0,1] neg_hi:[0,1]
	v_pk_add_f32 v[20:21], v[20:21], v[70:71] op_sel:[0,1] neg_lo:[0,1] neg_hi:[0,1]
	v_pk_mul_f32 v[18:19], v[18:19], v[72:73] op_sel_hi:[1,0]
	v_pk_mul_f32 v[20:21], v[20:21], v[72:73] op_sel_hi:[1,0]
	v_pk_add_f32 v[22:23], v[22:23], v[70:71] op_sel:[0,1] neg_lo:[0,1] neg_hi:[0,1]
	v_pk_add_f32 v[2:3], v[2:3], v[70:71] op_sel:[0,1] neg_lo:[0,1] neg_hi:[0,1]
	v_pk_mul_f32 v[22:23], v[22:23], v[72:73] op_sel_hi:[1,0]
	v_pk_mul_f32 v[2:3], v[2:3], v[72:73] op_sel_hi:[1,0]
	v_pk_add_f32 v[4:5], v[4:5], v[70:71] op_sel:[0,1] neg_lo:[0,1] neg_hi:[0,1]
	v_pk_add_f32 v[6:7], v[6:7], v[70:71] op_sel:[0,1] neg_lo:[0,1] neg_hi:[0,1]
	v_pk_mul_f32 v[4:5], v[4:5], v[72:73] op_sel_hi:[1,0]
	v_pk_mul_f32 v[6:7], v[6:7], v[72:73] op_sel_hi:[1,0]
	s_cmpk_lt_i32 s50, 0x200
	s_waitcnt vmcnt(30)
	v_pk_mul_f32 v[50:51], v[192:193], v[50:51]
	v_lshlrev_b32_e32 v66, 16, v82
	v_and_b32_e32 v67, 0xffff0000, v82
	v_pk_mul_f32 v[50:51], v[50:51], v[66:67]
	v_pk_mul_f32 v[52:53], v[194:195], v[52:53]
	v_lshlrev_b32_e32 v66, 16, v83
	v_and_b32_e32 v67, 0xffff0000, v83
	v_pk_mul_f32 v[52:53], v[52:53], v[66:67]
	v_cvt_pk_bf16_f32 v66, v50, v51
	v_cvt_pk_bf16_f32 v67, v52, v53
	v_lshl_add_u64 v[50:51], v[78:79], 0, v[140:141]
	global_store_dwordx2 v[50:51], v[66:67], off
	s_nop 0
	s_waitcnt vmcnt(29)
	v_pk_mul_f32 v[54:55], v[196:197], v[54:55]
	v_lshlrev_b32_e32 v66, 16, v84
	v_and_b32_e32 v67, 0xffff0000, v84
	v_pk_mul_f32 v[56:57], v[198:199], v[56:57]
	v_lshlrev_b32_e32 v52, 16, v85
	v_and_b32_e32 v53, 0xffff0000, v85
	v_pk_mul_f32 v[54:55], v[54:55], v[66:67]
	v_pk_mul_f32 v[52:53], v[56:57], v[52:53]
	v_cvt_pk_bf16_f32 v54, v54, v55
	v_cvt_pk_bf16_f32 v55, v52, v53
	global_store_dwordx2 v[50:51], v[54:55], off offset:16
	s_nop 0
	s_waitcnt vmcnt(28)
	v_pk_mul_f32 v[52:53], v[200:201], v[58:59]
	v_lshlrev_b32_e32 v58, 16, v86
	v_and_b32_e32 v59, 0xffff0000, v86
	v_pk_mul_f32 v[52:53], v[52:53], v[58:59]
	v_pk_add_f32 v[58:59], v[60:61], v[70:71] op_sel:[0,1] neg_lo:[0,1] neg_hi:[0,1]
	v_lshlrev_b32_e32 v56, 16, v87
	v_pk_mul_f32 v[58:59], v[58:59], v[72:73] op_sel_hi:[1,0]
	v_and_b32_e32 v57, 0xffff0000, v87
	v_pk_mul_f32 v[54:55], v[202:203], v[58:59]
	v_cvt_pk_bf16_f32 v52, v52, v53
	v_pk_mul_f32 v[54:55], v[54:55], v[56:57]
	v_pk_add_f32 v[58:59], v[62:63], v[70:71] op_sel:[0,1] neg_lo:[0,1] neg_hi:[0,1]
	v_cvt_pk_bf16_f32 v53, v54, v55
	global_store_dwordx2 v[50:51], v[52:53], off offset:32
	s_nop 0
	v_pk_mul_f32 v[58:59], v[58:59], v[72:73] op_sel_hi:[1,0]
	s_waitcnt vmcnt(27)
	v_pk_mul_f32 v[52:53], v[204:205], v[58:59]
	v_lshlrev_b32_e32 v58, 16, v88
	v_and_b32_e32 v59, 0xffff0000, v88
	v_pk_mul_f32 v[52:53], v[52:53], v[58:59]
	v_pk_add_f32 v[58:59], v[64:65], v[70:71] op_sel:[0,1] neg_lo:[0,1] neg_hi:[0,1]
	v_lshlrev_b32_e32 v56, 16, v89
	v_pk_mul_f32 v[58:59], v[58:59], v[72:73] op_sel_hi:[1,0]
	v_and_b32_e32 v57, 0xffff0000, v89
	v_pk_mul_f32 v[54:55], v[206:207], v[58:59]
	v_cvt_pk_bf16_f32 v52, v52, v53
	v_pk_mul_f32 v[54:55], v[54:55], v[56:57]
	s_nop 0
	v_cvt_pk_bf16_f32 v53, v54, v55
	global_store_dwordx2 v[50:51], v[52:53], off offset:48
	s_nop 0
	s_waitcnt vmcnt(26)
	v_pk_mul_f32 v[34:35], v[208:209], v[34:35]
	v_lshlrev_b32_e32 v52, 16, v90
	v_and_b32_e32 v53, 0xffff0000, v90
	v_pk_mul_f32 v[34:35], v[34:35], v[52:53]
	v_pk_mul_f32 v[36:37], v[210:211], v[36:37]
	v_lshlrev_b32_e32 v52, 16, v91
	v_and_b32_e32 v53, 0xffff0000, v91
	v_pk_mul_f32 v[36:37], v[36:37], v[52:53]
	v_cvt_pk_bf16_f32 v34, v34, v35
	v_cvt_pk_bf16_f32 v35, v36, v37
	global_store_dwordx2 v[50:51], v[34:35], off offset:64
	s_nop 0
	s_waitcnt vmcnt(25)
	v_pk_mul_f32 v[34:35], v[212:213], v[38:39]
	v_lshlrev_b32_e32 v38, 16, v92
	v_and_b32_e32 v39, 0xffff0000, v92
	v_pk_mul_f32 v[34:35], v[34:35], v[38:39]
	v_pk_add_f32 v[38:39], v[40:41], v[70:71] op_sel:[0,1] neg_lo:[0,1] neg_hi:[0,1]
	v_cvt_pk_bf16_f32 v34, v34, v35
	v_pk_mul_f32 v[38:39], v[38:39], v[72:73] op_sel_hi:[1,0]
	v_pk_add_f32 v[40:41], v[42:43], v[70:71] op_sel:[0,1] neg_lo:[0,1] neg_hi:[0,1]
	v_pk_mul_f32 v[36:37], v[214:215], v[38:39]
	v_lshlrev_b32_e32 v38, 16, v93
	v_and_b32_e32 v39, 0xffff0000, v93
	v_pk_mul_f32 v[36:37], v[36:37], v[38:39]
	v_pk_mul_f32 v[40:41], v[40:41], v[72:73] op_sel_hi:[1,0]
	v_cvt_pk_bf16_f32 v35, v36, v37
	global_store_dwordx2 v[50:51], v[34:35], off offset:80
	s_nop 0
	s_waitcnt vmcnt(24)
; __device__ __forceinline__ unsigned cvtpk(float lo, float hi) { f32x2_t v = {lo, hi}; bf16x2_t b = __builtin_convertvector(v, bf16x2_t); return __builtin_bit_cast(unsigned, b); }
; __device__ __forceinline__ float bflo(unsigned w) { return __uint_as_float(w << 16); }
; __device__ __forceinline__ float bfhi(unsigned w) { return __uint_as_float(w & 0xffff0000u); }
; __device__ __forceinline__ void ro_item2(int it0, LAS unsigned char* lds, const bf16_t* RQ, const bf16_t* RK, const bf16_t* RV, const bf16_t* RG, const bf16_t* SPREV, const float* GN, bf16_t* MIX,
;                                          int tid, int wid, int lane) {
;     ...
; #pragma unroll
;     for (int et = 0; et < 4; ++et)
; #pragma unroll
;         for (int g = 0; g < 4; ++g) {
;             const int e0 = 32 * et + 8 * g + 4 * hi;
;             const u32x2 gt = *(const u32x2*)(RG + qrow * 1024 + h * 128 + e0);
;             const f32x4 gn = *(const f32x4*)(GN + h * 128 + e0);
;             const float y0 = (o[et][4 * g] - mean) * rstd * gn[0] * bflo(gt.x), y1 = (o[et][4 * g + 1] - mean) * rstd * gn[1] * bfhi(gt.x);
;             const float y2 = (o[et][4 * g + 2] - mean) * rstd * gn[2] * bflo(gt.y), y3 = (o[et][4 * g + 3] - mean) * rstd * gn[3] * bfhi(gt.y);
;             u32x2 w; w.x = cvtpk(y0, y1); w.y = cvtpk(y2, y3);
;             *(u32x2*)(MIX + qrow * 2048 + h * 128 + e0) = w;
;         }
	v_pk_mul_f32 v[34:35], v[216:217], v[40:41]
	v_lshlrev_b32_e32 v40, 16, v94
	v_and_b32_e32 v41, 0xffff0000, v94
	v_pk_mul_f32 v[34:35], v[34:35], v[40:41]
	v_pk_add_f32 v[40:41], v[44:45], v[70:71] op_sel:[0,1] neg_lo:[0,1] neg_hi:[0,1]
	v_lshlrev_b32_e32 v38, 16, v95
	v_pk_mul_f32 v[40:41], v[40:41], v[72:73] op_sel_hi:[1,0]
	v_and_b32_e32 v39, 0xffff0000, v95
	v_pk_mul_f32 v[36:37], v[218:219], v[40:41]
	v_cvt_pk_bf16_f32 v34, v34, v35
	v_pk_mul_f32 v[36:37], v[36:37], v[38:39]
	v_pk_add_f32 v[40:41], v[46:47], v[70:71] op_sel:[0,1] neg_lo:[0,1] neg_hi:[0,1]
	v_cvt_pk_bf16_f32 v35, v36, v37
	global_store_dwordx2 v[50:51], v[34:35], off offset:96
	s_nop 0
	v_pk_mul_f32 v[40:41], v[40:41], v[72:73] op_sel_hi:[1,0]
	s_waitcnt vmcnt(23)
	v_pk_mul_f32 v[34:35], v[220:221], v[40:41]
	v_lshlrev_b32_e32 v40, 16, v96
	v_and_b32_e32 v41, 0xffff0000, v96
	v_pk_mul_f32 v[34:35], v[34:35], v[40:41]
	v_pk_add_f32 v[40:41], v[48:49], v[70:71] op_sel:[0,1] neg_lo:[0,1] neg_hi:[0,1]
	v_lshlrev_b32_e32 v38, 16, v97
	v_pk_mul_f32 v[40:41], v[40:41], v[72:73] op_sel_hi:[1,0]
	v_and_b32_e32 v39, 0xffff0000, v97
	v_pk_mul_f32 v[36:37], v[222:223], v[40:41]
	v_cvt_pk_bf16_f32 v34, v34, v35
	v_pk_mul_f32 v[36:37], v[36:37], v[38:39]
	s_nop 0
	v_cvt_pk_bf16_f32 v35, v36, v37
	global_store_dwordx2 v[50:51], v[34:35], off offset:112
	s_nop 0
	s_waitcnt vmcnt(22)
	v_pk_mul_f32 v[18:19], v[18:19], v[224:225]
	v_lshlrev_b32_e32 v34, 16, v98
	v_and_b32_e32 v35, 0xffff0000, v98
	v_pk_mul_f32 v[18:19], v[18:19], v[34:35]
	v_pk_mul_f32 v[20:21], v[20:21], v[226:227]
	v_lshlrev_b32_e32 v34, 16, v99
	v_and_b32_e32 v35, 0xffff0000, v99
	v_pk_mul_f32 v[20:21], v[20:21], v[34:35]
	v_cvt_pk_bf16_f32 v18, v18, v19
	v_cvt_pk_bf16_f32 v19, v20, v21
	global_store_dwordx2 v[50:51], v[18:19], off offset:128
	s_nop 0
	s_waitcnt vmcnt(21)
	v_pk_mul_f32 v[18:19], v[22:23], v[228:229]
	v_lshlrev_b32_e32 v22, 16, v100
	v_and_b32_e32 v23, 0xffff0000, v100
	v_pk_mul_f32 v[18:19], v[18:19], v[22:23]
	v_pk_add_f32 v[22:23], v[24:25], v[70:71] op_sel:[0,1] neg_lo:[0,1] neg_hi:[0,1]
	v_cvt_pk_bf16_f32 v18, v18, v19
	v_pk_mul_f32 v[22:23], v[22:23], v[72:73] op_sel_hi:[1,0]
	v_pk_add_f32 v[24:25], v[26:27], v[70:71] op_sel:[0,1] neg_lo:[0,1] neg_hi:[0,1]
	v_pk_mul_f32 v[20:21], v[22:23], v[230:231]
	v_lshlrev_b32_e32 v22, 16, v101
	v_and_b32_e32 v23, 0xffff0000, v101
	v_pk_mul_f32 v[20:21], v[20:21], v[22:23]
	v_pk_mul_f32 v[24:25], v[24:25], v[72:73] op_sel_hi:[1,0]
	v_cvt_pk_bf16_f32 v19, v20, v21
	global_store_dwordx2 v[50:51], v[18:19], off offset:144
	s_nop 0
	s_waitcnt vmcnt(20)
	v_pk_mul_f32 v[18:19], v[24:25], v[232:233]
	v_lshlrev_b32_e32 v24, 16, v102
	v_and_b32_e32 v25, 0xffff0000, v102
	v_pk_mul_f32 v[18:19], v[18:19], v[24:25]
	v_pk_add_f32 v[24:25], v[28:29], v[70:71] op_sel:[0,1] neg_lo:[0,1] neg_hi:[0,1]
	v_lshlrev_b32_e32 v22, 16, v103
	v_pk_mul_f32 v[24:25], v[24:25], v[72:73] op_sel_hi:[1,0]
	v_and_b32_e32 v23, 0xffff0000, v103
	v_pk_mul_f32 v[20:21], v[24:25], v[234:235]
	v_cvt_pk_bf16_f32 v18, v18, v19
	v_pk_mul_f32 v[20:21], v[20:21], v[22:23]
	v_pk_add_f32 v[24:25], v[30:31], v[70:71] op_sel:[0,1] neg_lo:[0,1] neg_hi:[0,1]
	v_cvt_pk_bf16_f32 v19, v20, v21
	global_store_dwordx2 v[50:51], v[18:19], off offset:160
	s_nop 0
	v_pk_mul_f32 v[24:25], v[24:25], v[72:73] op_sel_hi:[1,0]
	s_waitcnt vmcnt(19)
	v_pk_mul_f32 v[18:19], v[24:25], v[236:237]
	v_lshlrev_b32_e32 v24, 16, v104
	v_and_b32_e32 v25, 0xffff0000, v104
	v_pk_mul_f32 v[18:19], v[18:19], v[24:25]
	v_pk_add_f32 v[24:25], v[32:33], v[70:71] op_sel:[0,1] neg_lo:[0,1] neg_hi:[0,1]
	v_lshlrev_b32_e32 v22, 16, v105
	v_pk_mul_f32 v[24:25], v[24:25], v[72:73] op_sel_hi:[1,0]
	v_and_b32_e32 v23, 0xffff0000, v105
	v_pk_mul_f32 v[20:21], v[24:25], v[238:239]
	v_cvt_pk_bf16_f32 v18, v18, v19
	v_pk_mul_f32 v[20:21], v[20:21], v[22:23]
	s_nop 0
	v_cvt_pk_bf16_f32 v19, v20, v21
	global_store_dwordx2 v[50:51], v[18:19], off offset:176
	s_nop 0
	s_waitcnt vmcnt(18)
	v_pk_mul_f32 v[2:3], v[2:3], v[240:241]
	v_lshlrev_b32_e32 v18, 16, v106
	v_and_b32_e32 v19, 0xffff0000, v106
	v_pk_mul_f32 v[2:3], v[2:3], v[18:19]
	v_pk_mul_f32 v[4:5], v[4:5], v[242:243]
	v_lshlrev_b32_e32 v18, 16, v107
	v_and_b32_e32 v19, 0xffff0000, v107
	v_pk_mul_f32 v[4:5], v[4:5], v[18:19]
	v_cvt_pk_bf16_f32 v2, v2, v3
	v_cvt_pk_bf16_f32 v3, v4, v5
	global_store_dwordx2 v[50:51], v[2:3], off offset:192
	s_nop 0
	s_waitcnt vmcnt(17)
	v_pk_mul_f32 v[2:3], v[6:7], v[244:245]
	v_lshlrev_b32_e32 v6, 16, v108
	v_and_b32_e32 v7, 0xffff0000, v108
	v_pk_mul_f32 v[2:3], v[2:3], v[6:7]
	v_pk_add_f32 v[6:7], v[8:9], v[70:71] op_sel:[0,1] neg_lo:[0,1] neg_hi:[0,1]
	v_cvt_pk_bf16_f32 v2, v2, v3
	v_pk_mul_f32 v[6:7], v[6:7], v[72:73] op_sel_hi:[1,0]
	v_pk_add_f32 v[8:9], v[10:11], v[70:71] op_sel:[0,1] neg_lo:[0,1] neg_hi:[0,1]
	v_pk_mul_f32 v[4:5], v[6:7], v[246:247]
	v_lshlrev_b32_e32 v6, 16, v109
	v_and_b32_e32 v7, 0xffff0000, v109
	v_pk_mul_f32 v[4:5], v[4:5], v[6:7]
	v_pk_mul_f32 v[8:9], v[8:9], v[72:73] op_sel_hi:[1,0]
	v_cvt_pk_bf16_f32 v3, v4, v5
	global_store_dwordx2 v[50:51], v[2:3], off offset:208
	s_nop 0
	s_waitcnt vmcnt(16)
	v_pk_mul_f32 v[2:3], v[8:9], v[248:249]
	v_lshlrev_b32_e32 v8, 16, v110
	v_and_b32_e32 v9, 0xffff0000, v110
	v_pk_mul_f32 v[2:3], v[2:3], v[8:9]
	v_pk_add_f32 v[8:9], v[12:13], v[70:71] op_sel:[0,1] neg_lo:[0,1] neg_hi:[0,1]
	v_lshlrev_b32_e32 v6, 16, v111
	v_pk_mul_f32 v[8:9], v[8:9], v[72:73] op_sel_hi:[1,0]
	v_and_b32_e32 v7, 0xffff0000, v111
	v_pk_mul_f32 v[4:5], v[8:9], v[250:251]
	v_cvt_pk_bf16_f32 v2, v2, v3
	v_pk_mul_f32 v[4:5], v[4:5], v[6:7]
	v_pk_add_f32 v[8:9], v[14:15], v[70:71] op_sel:[0,1] neg_lo:[0,1] neg_hi:[0,1]
	v_cvt_pk_bf16_f32 v3, v4, v5
	global_store_dwordx2 v[50:51], v[2:3], off offset:224
	s_nop 0
	v_pk_mul_f32 v[8:9], v[8:9], v[72:73] op_sel_hi:[1,0]
	s_waitcnt vmcnt(15)
	v_pk_mul_f32 v[2:3], v[8:9], v[180:181]
	v_lshlrev_b32_e32 v8, 16, v112
	v_and_b32_e32 v9, 0xffff0000, v112
	v_pk_mul_f32 v[2:3], v[2:3], v[8:9]
	v_pk_add_f32 v[8:9], v[16:17], v[70:71] op_sel:[0,1] neg_lo:[0,1] neg_hi:[0,1]
	v_lshlrev_b32_e32 v6, 16, v113
	v_pk_mul_f32 v[8:9], v[8:9], v[72:73] op_sel_hi:[1,0]
	v_and_b32_e32 v7, 0xffff0000, v113
	v_pk_mul_f32 v[4:5], v[8:9], v[182:183]
	v_cvt_pk_bf16_f32 v2, v2, v3
	v_pk_mul_f32 v[4:5], v[4:5], v[6:7]
	s_nop 0
	v_cvt_pk_bf16_f32 v3, v4, v5
	global_store_dwordx2 v[50:51], v[2:3], off offset:240
	s_cbranch_scc0 .LBB0_1246
